# attn0 plain loop VALU trims: rescale factor computed only on the rare threshold-crossing path (out of line), NaN-canonicalising self-max ops dropped, threshold constant folded; rolling counted lgkmcnt
# speedup vs baseline: 1.0286x; 1.0135x over previous
.LBB0_309:
	s_mov_b32 s77, s74
	v_add3_u32 v215, s77, v209, v208
	v_add3_u32 v216, s77, v210, v208
	v_add3_u32 v233, s77, v211, v208
	v_add3_u32 v254, s77, v212, v208
	ds_read_b128 v[234:237], v215 offset:49152
	ds_read_b128 v[238:241], v215 offset:57344
	ds_read_b128 v[242:245], v216 offset:49152
	ds_read_b128 v[246:249], v216 offset:57344
	ds_read_b128 v[250:253], v233 offset:49152
	s_add_u32 s4, s70, 0xffffc000
	s_mov_b32 s74, s72
	s_addc_u32 s5, s71, -1
	s_add_i32 s72, s72, s42
	s_setprio 1
	s_waitcnt lgkmcnt(4)
	v_mfma_f32_32x32x16_bf16 v[112:127], v[234:237], v[188:191], 0
	ds_read_b128 v[234:237], v233 offset:57344
	v_add_f32_e32 v1, 0, v230
	v_add_f32_e32 v1, v232, v1
	v_add_f32_e32 v1, v228, v1
	v_add_f32_e32 v1, v231, v1
	v_add_f32_e32 v1, v226, v1
	v_add_f32_e32 v1, v229, v1
	s_waitcnt lgkmcnt(4)
	v_mfma_f32_32x32x16_bf16 v[96:111], v[238:241], v[188:191], 0
	ds_read_b128 v[238:241], v254 offset:49152
	v_add_f32_e32 v1, v225, v1
	v_add_f32_e32 v1, v227, v1
	v_add_f32_e32 v1, v222, v1
	v_add_f32_e32 v1, v224, v1
	v_add_f32_e32 v1, v220, v1
	s_waitcnt lgkmcnt(4)
	v_mfma_f32_32x32x16_bf16 v[112:127], v[242:245], v[184:187], v[112:127]
	ds_read_b128 v[242:245], v254 offset:57344
	s_mov_b32 s73, m0
	s_mov_b32 m0, s72
	s_nop 0
	global_load_lds_dwordx4 v197, s[4:5]
	s_mov_b32 m0, s73
	v_add_f32_e32 v1, v223, v1
	v_exp_f32_e32 v2, v128
	v_add_f32_e32 v1, v218, v1
	v_exp_f32_e32 v12, v129
	s_waitcnt lgkmcnt(4)
	v_mfma_f32_32x32x16_bf16 v[96:111], v[246:249], v[184:187], v[96:111]
	ds_read_b128 v[246:249], v215 offset:49280
	v_add_f32_e32 v1, v221, v1
	v_exp_f32_e32 v13, v130
	v_add_f32_e32 v1, v217, v1
	v_exp_f32_e32 v14, v131
	s_waitcnt lgkmcnt(4)
	v_mfma_f32_32x32x16_bf16 v[112:127], v[250:253], v[180:183], v[112:127]
	ds_read_b128 v[250:253], v215 offset:57472
	v_add_f32_e32 v1, v219, v1
	v_exp_f32_e32 v15, v132
	v_add_f32_e32 v1, v2, v1
	v_exp_f32_e32 v18, v133
	s_waitcnt lgkmcnt(4)
	v_mfma_f32_32x32x16_bf16 v[96:111], v[234:237], v[180:183], v[96:111]
	ds_read_b128 v[234:237], v216 offset:49280
	s_addk_i32 s72, 0x400
	s_mov_b32 s73, m0
	s_mov_b32 m0, s72
	s_nop 0
	global_load_lds_dwordx4 v198, s[4:5]
	s_mov_b32 m0, s73
	v_add_f32_e32 v1, v12, v1
	v_exp_f32_e32 v19, v134
	v_add_f32_e32 v1, v13, v1
	s_waitcnt lgkmcnt(4)
	v_mfma_f32_32x32x16_bf16 v[112:127], v[238:241], v[176:179], v[112:127]
	ds_read_b128 v[238:241], v216 offset:57472
	v_exp_f32_e32 v20, v135
	v_add_f32_e32 v1, v14, v1
	v_exp_f32_e32 v21, v136
	v_add_f32_e32 v1, v15, v1
	s_waitcnt lgkmcnt(4)
	v_mfma_f32_32x32x16_bf16 v[96:111], v[242:245], v[176:179], v[96:111]
	ds_read_b128 v[242:245], v233 offset:49280
	v_exp_f32_e32 v22, v137
	v_add_f32_e32 v1, v18, v1
	v_exp_f32_e32 v23, v138
	v_add_f32_e32 v1, v19, v1
	s_waitcnt lgkmcnt(4)
	v_mfma_f32_32x32x16_bf16 v[112:127], v[246:249], v[172:175], v[112:127]
	ds_read_b128 v[246:249], v233 offset:57472
	s_add_i32 s4, s69, s97
	s_mov_b32 s5, m0
	s_mov_b32 m0, s4
	s_nop 0
	global_load_lds_dwordx4 v199, s[56:57]
	s_mov_b32 m0, s5
	v_exp_f32_e32 v24, v139
	v_add_f32_e32 v1, v20, v1
	v_exp_f32_e32 v25, v140
	v_add_f32_e32 v1, v21, v1
	s_waitcnt lgkmcnt(4)
	v_mfma_f32_32x32x16_bf16 v[96:111], v[250:253], v[172:175], v[96:111]
	ds_read_b128 v[250:253], v254 offset:49280
	v_exp_f32_e32 v26, v141
	v_add_f32_e32 v1, v22, v1
	v_exp_f32_e32 v27, v142
	v_add_f32_e32 v1, v23, v1
	s_waitcnt lgkmcnt(4)
	v_mfma_f32_32x32x16_bf16 v[112:127], v[234:237], v[168:171], v[112:127]
	ds_read_b128 v[234:237], v254 offset:57472
	v_exp_f32_e32 v28, v143
	v_add_f32_e32 v1, v24, v1
	v_add_f32_e32 v1, v25, v1
	v_add_f32_e32 v1, v26, v1
	s_waitcnt lgkmcnt(4)
	v_mfma_f32_32x32x16_bf16 v[96:111], v[238:241], v[168:171], v[96:111]
	s_addk_i32 s4, 0x400
	s_mov_b32 s5, m0
	s_mov_b32 m0, s4
	s_nop 0
	global_load_lds_dwordx4 v200, s[56:57]
	s_mov_b32 m0, s5
	v_add_f32_e32 v1, v27, v1
	v_add_f32_e32 v1, v28, v1
	v_mov_b32_e32 v3, v1
	v_cvt_pk_bf16_f32 v4, v230, v232
	v_cvt_pk_bf16_f32 v5, v228, v231
	v_cvt_pk_bf16_f32 v6, v226, v229
	s_waitcnt lgkmcnt(3)
	v_mfma_f32_32x32x16_bf16 v[112:127], v[242:245], v[164:167], v[112:127]
	s_nop 1
	v_permlane32_swap_b32_e32 v1, v3
	v_cvt_pk_bf16_f32 v7, v225, v227
	v_permlane32_swap_b32_e32 v4, v6
	v_cvt_pk_bf16_f32 v8, v222, v224
	v_cvt_pk_bf16_f32 v9, v220, v223
	s_waitcnt lgkmcnt(2)
	v_mfma_f32_32x32x16_bf16 v[96:111], v[246:249], v[164:167], v[96:111]
	v_cvt_pk_bf16_f32 v10, v218, v221
	v_cvt_pk_bf16_f32 v11, v217, v219
	v_cvt_pk_bf16_f32 v12, v2, v12
	v_cvt_pk_bf16_f32 v13, v13, v14
	v_cvt_pk_bf16_f32 v14, v15, v18
	v_cvt_pk_bf16_f32 v15, v19, v20
	s_waitcnt lgkmcnt(1)
	v_mfma_f32_32x32x16_bf16 v[112:127], v[250:253], v[160:163], v[112:127]
	v_cvt_pk_bf16_f32 v18, v21, v22
	v_cvt_pk_bf16_f32 v19, v23, v24
	v_cvt_pk_bf16_f32 v20, v25, v26
	v_cvt_pk_bf16_f32 v21, v27, v28
	v_permlane32_swap_b32_e32 v5, v7
	s_waitcnt lgkmcnt(0)
	v_mfma_f32_32x32x16_bf16 v[96:111], v[234:237], v[160:163], v[96:111]
	v_permlane32_swap_b32_e32 v8, v10
	v_permlane32_swap_b32_e32 v9, v11
	v_permlane32_swap_b32_e32 v12, v14
	v_permlane32_swap_b32_e32 v13, v15
	v_permlane32_swap_b32_e32 v18, v20
	v_permlane32_swap_b32_e32 v19, v21
	s_setprio 0
	v_add_u32_e32 v2, s74, v206
	ds_read_b64_tr_b16 v[22:23], v2 offset:0
	ds_read_b64_tr_b16 v[24:25], v2 offset:0x800
	ds_read_b64_tr_b16 v[26:27], v2 offset:0x1000
	ds_read_b64_tr_b16 v[28:29], v2 offset:0x1800
	ds_read_b64_tr_b16 v[128:129], v2 offset:0x2000
	ds_read_b64_tr_b16 v[130:131], v2 offset:0x2800
	ds_read_b64_tr_b16 v[132:133], v2 offset:0x3000
	ds_read_b64_tr_b16 v[134:135], v2 offset:0x3800
	s_waitcnt lgkmcnt(6)
	s_nop 0
	v_mfma_f32_32x32x16_bf16 v[32:47], v[4:7], v[22:25], v[32:47]
	ds_read_b64_tr_b16 v[22:23], v2 offset:0x200
	ds_read_b64_tr_b16 v[24:25], v2 offset:0xa00
	s_waitcnt lgkmcnt(6)
	v_mfma_f32_32x32x16_bf16 v[32:47], v[8:11], v[26:29], v[32:47]
	ds_read_b64_tr_b16 v[26:27], v2 offset:0x1200
	ds_read_b64_tr_b16 v[28:29], v2 offset:0x1a00
	s_waitcnt lgkmcnt(6)
	v_mfma_f32_32x32x16_bf16 v[32:47], v[12:15], v[128:131], v[32:47]
	ds_read_b64_tr_b16 v[128:129], v2 offset:0x2200
	ds_read_b64_tr_b16 v[130:131], v2 offset:0x2a00
	s_waitcnt lgkmcnt(6)
	v_mfma_f32_32x32x16_bf16 v[32:47], v[18:21], v[132:135], v[32:47]
	ds_read_b64_tr_b16 v[132:133], v2 offset:0x3200
	ds_read_b64_tr_b16 v[134:135], v2 offset:0x3a00
	s_waitcnt lgkmcnt(6)
	v_mfma_f32_32x32x16_bf16 v[48:63], v[4:7], v[22:25], v[48:63]
	ds_read_b64_tr_b16 v[22:23], v2 offset:0x400
	ds_read_b64_tr_b16 v[24:25], v2 offset:0xc00
	s_waitcnt lgkmcnt(6)
	v_mfma_f32_32x32x16_bf16 v[48:63], v[8:11], v[26:29], v[48:63]
	ds_read_b64_tr_b16 v[26:27], v2 offset:0x1400
	ds_read_b64_tr_b16 v[28:29], v2 offset:0x1c00
	s_waitcnt lgkmcnt(6)
	v_mfma_f32_32x32x16_bf16 v[48:63], v[12:15], v[128:131], v[48:63]
	ds_read_b64_tr_b16 v[128:129], v2 offset:0x2400
	ds_read_b64_tr_b16 v[130:131], v2 offset:0x2c00
	s_waitcnt lgkmcnt(6)
	v_mfma_f32_32x32x16_bf16 v[48:63], v[18:21], v[132:135], v[48:63]
	ds_read_b64_tr_b16 v[132:133], v2 offset:0x3400
	ds_read_b64_tr_b16 v[134:135], v2 offset:0x3c00
	s_waitcnt lgkmcnt(6)
	v_mfma_f32_32x32x16_bf16 v[64:79], v[4:7], v[22:25], v[64:79]
	ds_read_b64_tr_b16 v[22:23], v2 offset:0x600
	ds_read_b64_tr_b16 v[24:25], v2 offset:0xe00
	s_waitcnt lgkmcnt(6)
	v_mfma_f32_32x32x16_bf16 v[64:79], v[8:11], v[26:29], v[64:79]
	ds_read_b64_tr_b16 v[26:27], v2 offset:0x1600
	ds_read_b64_tr_b16 v[28:29], v2 offset:0x1e00
	s_waitcnt lgkmcnt(6)
	v_mfma_f32_32x32x16_bf16 v[64:79], v[12:15], v[128:131], v[64:79]
	ds_read_b64_tr_b16 v[128:129], v2 offset:0x2600
	ds_read_b64_tr_b16 v[130:131], v2 offset:0x2e00
	s_waitcnt lgkmcnt(6)
	v_mfma_f32_32x32x16_bf16 v[64:79], v[18:21], v[132:135], v[64:79]
	ds_read_b64_tr_b16 v[132:133], v2 offset:0x3600
	ds_read_b64_tr_b16 v[134:135], v2 offset:0x3e00
	s_waitcnt lgkmcnt(6)
	v_mfma_f32_32x32x16_bf16 v[80:95], v[4:7], v[22:25], v[80:95]
	v_max_f32_e32 v2, v113, v112
	v_max3_f32 v2, v2, v114, v115
	v_max3_f32 v2, v2, v116, v117
	v_max3_f32 v2, v2, v118, v119
	v_max3_f32 v2, v2, v120, v121
	v_max3_f32 v2, v2, v122, v123
	v_max3_f32 v2, v2, v124, v125
	v_max3_f32 v2, v2, v126, v127
	s_waitcnt lgkmcnt(4)
	v_mfma_f32_32x32x16_bf16 v[80:95], v[8:11], v[26:29], v[80:95]
	v_max3_f32 v2, v2, v96, v97
	v_max3_f32 v2, v2, v98, v99
	v_max3_f32 v2, v2, v100, v101
	v_max3_f32 v2, v2, v102, v103
	v_max3_f32 v2, v2, v104, v105
	v_max3_f32 v2, v2, v106, v107
	v_max3_f32 v2, v2, v108, v109
	v_max3_f32 v2, v2, v110, v111
	s_waitcnt lgkmcnt(2)
	v_mfma_f32_32x32x16_bf16 v[80:95], v[12:15], v[128:131], v[80:95]
	v_mov_b32_e32 v4, v2
	s_nop 1
	v_permlane32_swap_b32_e32 v2, v4
	v_max_f32_e32 v2, v4, v2
	v_sub_f32_e32 v4, v2, v214
	v_cmp_ge_f32_e32 vcc, 0x42b504f3, v4
	v_max_f32_e32 v2, v214, v2
	s_waitcnt lgkmcnt(0)
	v_mfma_f32_32x32x16_bf16 v[80:95], v[18:21], v[132:135], v[80:95]
	s_cmp_eq_u64 vcc, exec
	s_cbranch_scc0 .Lattn0_slowA
	v_mov_b32_e32 v4, 1.0
	v_mov_b32_e32 v2, v214
.Lattn0_backA:
	s_waitcnt vmcnt(4) lgkmcnt(0)
	s_barrier
	v_add3_u32 v215, s69, v209, v208
	v_add3_u32 v216, s69, v210, v208
	v_add3_u32 v233, s69, v211, v208
	v_add3_u32 v254, s69, v212, v208
	ds_read_b128 v[234:237], v215 offset:49152
	ds_read_b128 v[238:241], v215 offset:57344
	ds_read_b128 v[242:245], v216 offset:49152
	ds_read_b128 v[246:249], v216 offset:57344
	ds_read_b128 v[250:253], v233 offset:49152
	v_mul_f32_e32 v5, 0xbe0293ee, v2
	v_fmamk_f32 v6, v112, 0x3e0293ee, v5
	v_fmamk_f32 v7, v113, 0x3e0293ee, v5
	v_fmamk_f32 v8, v114, 0x3e0293ee, v5
	v_fmamk_f32 v9, v115, 0x3e0293ee, v5
	v_fmamk_f32 v10, v116, 0x3e0293ee, v5
	v_fmamk_f32 v11, v117, 0x3e0293ee, v5
	v_fmamk_f32 v12, v118, 0x3e0293ee, v5
	v_fmamk_f32 v13, v119, 0x3e0293ee, v5
	v_fmamk_f32 v14, v120, 0x3e0293ee, v5
	v_fmamk_f32 v15, v121, 0x3e0293ee, v5
	v_fmamk_f32 v18, v122, 0x3e0293ee, v5
	v_fmamk_f32 v19, v123, 0x3e0293ee, v5
	v_fmamk_f32 v20, v124, 0x3e0293ee, v5
	v_fmamk_f32 v21, v125, 0x3e0293ee, v5
	v_fmamk_f32 v22, v126, 0x3e0293ee, v5
	v_fmamk_f32 v23, v127, 0x3e0293ee, v5
	v_fmamk_f32 v24, v96, 0x3e0293ee, v5
	v_fmamk_f32 v25, v97, 0x3e0293ee, v5
	v_fmamk_f32 v26, v98, 0x3e0293ee, v5
	v_fmamk_f32 v27, v99, 0x3e0293ee, v5
	v_fmamk_f32 v28, v100, 0x3e0293ee, v5
	v_fmamk_f32 v29, v101, 0x3e0293ee, v5
	v_fmamk_f32 v30, v102, 0x3e0293ee, v5
	v_fmamk_f32 v31, v103, 0x3e0293ee, v5
	v_fmamk_f32 v128, v104, 0x3e0293ee, v5
	v_fmamk_f32 v129, v105, 0x3e0293ee, v5
	v_fmamk_f32 v130, v106, 0x3e0293ee, v5
	v_fmamk_f32 v131, v107, 0x3e0293ee, v5
	v_fmamk_f32 v132, v108, 0x3e0293ee, v5
	v_fmamk_f32 v133, v109, 0x3e0293ee, v5
	v_fmamk_f32 v134, v110, 0x3e0293ee, v5
	v_fmac_f32_e32 v5, 0x3e0293ee, v111
	s_setprio 1
	s_waitcnt lgkmcnt(4)
	v_mfma_f32_32x32x16_bf16 v[112:127], v[234:237], v[188:191], 0
	ds_read_b128 v[234:237], v233 offset:57344
	v_exp_f32_e32 v135, v6
	v_exp_f32_e32 v136, v7
	v_exp_f32_e32 v137, v8
	v_exp_f32_e32 v138, v9
	s_waitcnt lgkmcnt(4)
	v_mfma_f32_32x32x16_bf16 v[96:111], v[238:241], v[188:191], 0
	ds_read_b128 v[238:241], v254 offset:49152
	v_exp_f32_e32 v10, v10
	v_exp_f32_e32 v11, v11
	v_exp_f32_e32 v12, v12
	v_exp_f32_e32 v13, v13
	s_waitcnt lgkmcnt(4)
	v_mfma_f32_32x32x16_bf16 v[112:127], v[242:245], v[184:187], v[112:127]
	ds_read_b128 v[242:245], v254 offset:57344
	s_add_i32 s4, s77, s42
	s_mov_b32 s5, m0
	s_mov_b32 m0, s4
	s_nop 0
	global_load_lds_dwordx4 v197, s[70:71]
	s_mov_b32 m0, s5
	v_exp_f32_e32 v14, v14
	v_exp_f32_e32 v15, v15
	v_exp_f32_e32 v18, v18
	s_waitcnt lgkmcnt(4)
	v_mfma_f32_32x32x16_bf16 v[96:111], v[246:249], v[184:187], v[96:111]
	ds_read_b128 v[246:249], v215 offset:49280
	v_exp_f32_e32 v19, v19
	v_exp_f32_e32 v20, v20
	v_exp_f32_e32 v21, v21
	v_exp_f32_e32 v22, v22
	s_waitcnt lgkmcnt(4)
	v_mfma_f32_32x32x16_bf16 v[112:127], v[250:253], v[180:183], v[112:127]
	ds_read_b128 v[250:253], v215 offset:57472
	v_exp_f32_e32 v23, v23
	v_exp_f32_e32 v7, v24
	v_exp_f32_e32 v24, v25
	v_exp_f32_e32 v25, v26
	s_waitcnt lgkmcnt(4)
	v_mfma_f32_32x32x16_bf16 v[96:111], v[234:237], v[180:183], v[96:111]
	ds_read_b128 v[234:237], v216 offset:49280
	s_addk_i32 s4, 0x400
	s_mov_b32 s5, m0
	s_mov_b32 m0, s4
	s_nop 0
	global_load_lds_dwordx4 v198, s[70:71]
	s_mov_b32 m0, s5
	v_exp_f32_e32 v26, v27
	v_exp_f32_e32 v27, v28
	v_exp_f32_e32 v28, v29
	v_exp_f32_e32 v29, v30
	s_waitcnt lgkmcnt(4)
	v_mfma_f32_32x32x16_bf16 v[112:127], v[238:241], v[176:179], v[112:127]
	ds_read_b128 v[238:241], v216 offset:57472
	v_exp_f32_e32 v30, v31
	v_exp_f32_e32 v31, v128
	v_exp_f32_e32 v128, v129
	v_exp_f32_e32 v129, v130
	s_waitcnt lgkmcnt(4)
	v_mfma_f32_32x32x16_bf16 v[96:111], v[242:245], v[176:179], v[96:111]
	ds_read_b128 v[242:245], v233 offset:49280
	v_exp_f32_e32 v130, v131
	v_exp_f32_e32 v131, v132
	v_exp_f32_e32 v132, v133
	v_exp_f32_e32 v133, v134
	s_waitcnt lgkmcnt(4)
	v_mfma_f32_32x32x16_bf16 v[112:127], v[246:249], v[172:175], v[112:127]
	ds_read_b128 v[246:249], v233 offset:57472
	s_add_u32 s4, s56, 0x4000
	s_addc_u32 s5, s57, 0
	s_add_i32 s72, s74, s97
	s_mov_b32 s73, m0
	s_mov_b32 m0, s72
	s_nop 0
	global_load_lds_dwordx4 v199, s[4:5]
	s_mov_b32 m0, s73
	v_exp_f32_e32 v134, v5
	v_add_f32_e32 v5, 0, v135
	v_add_f32_e32 v5, v136, v5
	v_add_f32_e32 v5, v137, v5
	v_add_f32_e32 v5, v138, v5
	v_add_f32_e32 v5, v10, v5
	s_waitcnt lgkmcnt(4)
	v_mfma_f32_32x32x16_bf16 v[96:111], v[250:253], v[172:175], v[96:111]
	ds_read_b128 v[250:253], v254 offset:49280
	v_add_f32_e32 v5, v11, v5
	v_add_f32_e32 v5, v12, v5
	v_add_f32_e32 v5, v13, v5
	v_add_f32_e32 v5, v14, v5
	v_add_f32_e32 v5, v15, v5
	v_add_f32_e32 v5, v18, v5
	v_add_f32_e32 v5, v19, v5
	v_add_f32_e32 v5, v20, v5
	s_waitcnt lgkmcnt(4)
	v_mfma_f32_32x32x16_bf16 v[112:127], v[234:237], v[168:171], v[112:127]
	ds_read_b128 v[234:237], v254 offset:57472
	v_add_f32_e32 v5, v21, v5
	v_add_f32_e32 v5, v22, v5
	v_add_f32_e32 v5, v23, v5
	v_add_f32_e32 v5, v7, v5
	v_add_f32_e32 v5, v24, v5
	v_add_f32_e32 v5, v25, v5
	v_add_f32_e32 v5, v26, v5
	s_waitcnt lgkmcnt(4)
	v_mfma_f32_32x32x16_bf16 v[96:111], v[238:241], v[168:171], v[96:111]
	s_addk_i32 s72, 0x400
	s_mov_b32 s73, m0
	s_mov_b32 m0, s72
	s_nop 0
	global_load_lds_dwordx4 v200, s[4:5]
	s_mov_b32 m0, s73
	v_add_f32_e32 v5, v27, v5
	v_add_f32_e32 v5, v28, v5
	v_add_f32_e32 v5, v29, v5
	v_add_f32_e32 v5, v30, v5
	v_add_f32_e32 v5, v31, v5
	v_add_f32_e32 v5, v128, v5
	v_add_f32_e32 v5, v129, v5
	v_add_f32_e32 v5, v130, v5
	s_waitcnt lgkmcnt(3)
	v_mfma_f32_32x32x16_bf16 v[112:127], v[242:245], v[164:167], v[112:127]
	v_add_f32_e32 v5, v131, v5
	v_add_f32_e32 v5, v132, v5
	v_add_f32_e32 v5, v133, v5
	v_add_f32_e32 v5, v134, v5
	v_mov_b32_e32 v6, v5
	v_cvt_pk_bf16_f32 v8, v135, v136
	v_cvt_pk_bf16_f32 v9, v137, v138
	v_cvt_pk_bf16_f32 v10, v10, v11
	s_waitcnt lgkmcnt(2)
	v_mfma_f32_32x32x16_bf16 v[96:111], v[246:249], v[164:167], v[96:111]
	s_nop 1
	v_permlane32_swap_b32_e32 v5, v6
	v_cvt_pk_bf16_f32 v11, v12, v13
	v_permlane32_swap_b32_e32 v8, v10
	v_cvt_pk_bf16_f32 v12, v14, v15
	v_cvt_pk_bf16_f32 v13, v18, v19
	v_cvt_pk_bf16_f32 v14, v20, v21
	v_cvt_pk_bf16_f32 v15, v22, v23
	s_waitcnt lgkmcnt(1)
	v_mfma_f32_32x32x16_bf16 v[112:127], v[250:253], v[160:163], v[112:127]
	v_cvt_pk_bf16_f32 v18, v7, v24
	v_cvt_pk_bf16_f32 v19, v25, v26
	v_cvt_pk_bf16_f32 v20, v27, v28
	v_cvt_pk_bf16_f32 v21, v29, v30
	v_cvt_pk_bf16_f32 v22, v31, v128
	v_cvt_pk_bf16_f32 v23, v129, v130
	v_cvt_pk_bf16_f32 v24, v131, v132
	s_waitcnt lgkmcnt(0)
	v_mfma_f32_32x32x16_bf16 v[96:111], v[234:237], v[160:163], v[96:111]
	v_cvt_pk_bf16_f32 v25, v133, v134
	v_permlane32_swap_b32_e32 v9, v11
	v_permlane32_swap_b32_e32 v12, v14
	v_permlane32_swap_b32_e32 v13, v15
	v_permlane32_swap_b32_e32 v18, v20
	v_permlane32_swap_b32_e32 v19, v21
	v_permlane32_swap_b32_e32 v22, v24
	v_permlane32_swap_b32_e32 v23, v25
	s_setprio 0
	v_add_u32_e32 v7, s77, v206
	ds_read_b64_tr_b16 v[26:27], v7 offset:0
	ds_read_b64_tr_b16 v[28:29], v7 offset:0x800
	ds_read_b64_tr_b16 v[128:129], v7 offset:0x1000
	ds_read_b64_tr_b16 v[130:131], v7 offset:0x1800
	ds_read_b64_tr_b16 v[132:133], v7 offset:0x2000
	ds_read_b64_tr_b16 v[134:135], v7 offset:0x2800
	ds_read_b64_tr_b16 v[136:137], v7 offset:0x3000
	ds_read_b64_tr_b16 v[138:139], v7 offset:0x3800
	s_waitcnt lgkmcnt(6)
	s_nop 0
	v_mfma_f32_32x32x16_bf16 v[32:47], v[8:11], v[26:29], v[32:47]
	ds_read_b64_tr_b16 v[26:27], v7 offset:0x200
	ds_read_b64_tr_b16 v[28:29], v7 offset:0xa00
	s_waitcnt lgkmcnt(6)
	v_mfma_f32_32x32x16_bf16 v[32:47], v[12:15], v[128:131], v[32:47]
	ds_read_b64_tr_b16 v[128:129], v7 offset:0x1200
	ds_read_b64_tr_b16 v[130:131], v7 offset:0x1a00
	s_waitcnt lgkmcnt(6)
	v_mfma_f32_32x32x16_bf16 v[32:47], v[18:21], v[132:135], v[32:47]
	ds_read_b64_tr_b16 v[132:133], v7 offset:0x2200
	ds_read_b64_tr_b16 v[134:135], v7 offset:0x2a00
	s_waitcnt lgkmcnt(6)
	v_mfma_f32_32x32x16_bf16 v[32:47], v[22:25], v[136:139], v[32:47]
	ds_read_b64_tr_b16 v[136:137], v7 offset:0x3200
	ds_read_b64_tr_b16 v[138:139], v7 offset:0x3a00
	s_waitcnt lgkmcnt(6)
	v_mfma_f32_32x32x16_bf16 v[48:63], v[8:11], v[26:29], v[48:63]
	ds_read_b64_tr_b16 v[26:27], v7 offset:0x400
	ds_read_b64_tr_b16 v[28:29], v7 offset:0xc00
	s_waitcnt lgkmcnt(6)
	v_mfma_f32_32x32x16_bf16 v[48:63], v[12:15], v[128:131], v[48:63]
	ds_read_b64_tr_b16 v[128:129], v7 offset:0x1400
	ds_read_b64_tr_b16 v[130:131], v7 offset:0x1c00
	s_waitcnt lgkmcnt(6)
	v_mfma_f32_32x32x16_bf16 v[48:63], v[18:21], v[132:135], v[48:63]
	ds_read_b64_tr_b16 v[132:133], v7 offset:0x2400
	ds_read_b64_tr_b16 v[134:135], v7 offset:0x2c00
	s_waitcnt lgkmcnt(6)
	v_mfma_f32_32x32x16_bf16 v[48:63], v[22:25], v[136:139], v[48:63]
	ds_read_b64_tr_b16 v[136:137], v7 offset:0x3400
	ds_read_b64_tr_b16 v[138:139], v7 offset:0x3c00
	s_waitcnt lgkmcnt(6)
	v_mfma_f32_32x32x16_bf16 v[64:79], v[8:11], v[26:29], v[64:79]
	ds_read_b64_tr_b16 v[26:27], v7 offset:0x600
	ds_read_b64_tr_b16 v[28:29], v7 offset:0xe00
	s_waitcnt lgkmcnt(6)
	v_mfma_f32_32x32x16_bf16 v[64:79], v[12:15], v[128:131], v[64:79]
	ds_read_b64_tr_b16 v[128:129], v7 offset:0x1600
	ds_read_b64_tr_b16 v[130:131], v7 offset:0x1e00
	s_waitcnt lgkmcnt(6)
	v_mfma_f32_32x32x16_bf16 v[64:79], v[18:21], v[132:135], v[64:79]
	ds_read_b64_tr_b16 v[132:133], v7 offset:0x2600
	ds_read_b64_tr_b16 v[134:135], v7 offset:0x2e00
	s_waitcnt lgkmcnt(6)
	v_mfma_f32_32x32x16_bf16 v[64:79], v[22:25], v[136:139], v[64:79]
	ds_read_b64_tr_b16 v[136:137], v7 offset:0x3600
	ds_read_b64_tr_b16 v[138:139], v7 offset:0x3e00
	s_waitcnt lgkmcnt(6)
	v_mfma_f32_32x32x16_bf16 v[80:95], v[8:11], v[26:29], v[80:95]
	v_max_f32_e32 v7, v113, v112
	v_max3_f32 v7, v7, v114, v115
	v_max3_f32 v7, v7, v116, v117
	v_max3_f32 v7, v7, v118, v119
	v_max3_f32 v7, v7, v120, v121
	v_max3_f32 v7, v7, v122, v123
	v_max3_f32 v7, v7, v124, v125
	v_max3_f32 v7, v7, v126, v127
	s_waitcnt lgkmcnt(4)
	v_mfma_f32_32x32x16_bf16 v[80:95], v[12:15], v[128:131], v[80:95]
	v_max3_f32 v7, v7, v96, v97
	v_max3_f32 v7, v7, v98, v99
	v_max3_f32 v7, v7, v100, v101
	v_max3_f32 v7, v7, v102, v103
	v_max3_f32 v7, v7, v104, v105
	v_max3_f32 v7, v7, v106, v107
	v_max3_f32 v7, v7, v108, v109
	v_max3_f32 v7, v7, v110, v111
	s_waitcnt lgkmcnt(2)
	v_mfma_f32_32x32x16_bf16 v[80:95], v[18:21], v[132:135], v[80:95]
	v_mov_b32_e32 v8, v7
	s_nop 1
	v_permlane32_swap_b32_e32 v7, v8
	v_max_f32_e32 v7, v8, v7
	v_sub_f32_e32 v8, v7, v2
	v_cmp_ge_f32_e32 vcc, 0x42b504f3, v8
	v_max_f32_e32 v8, v2, v7
	s_waitcnt lgkmcnt(0)
	v_mfma_f32_32x32x16_bf16 v[80:95], v[22:25], v[136:139], v[80:95]
	s_cmp_eq_u64 vcc, exec
	s_cbranch_scc0 .Lattn0_slowB
	v_mov_b32_e32 v7, 1.0
	v_mov_b32_e32 v214, v2
.Lattn0_backB:
	v_mul_f32_e32 v2, 0xbe0293ee, v214
	v_fmamk_f32 v8, v112, 0x3e0293ee, v2
	v_fmamk_f32 v9, v113, 0x3e0293ee, v2
	v_fmamk_f32 v10, v114, 0x3e0293ee, v2
	v_fmamk_f32 v11, v115, 0x3e0293ee, v2
	v_fmamk_f32 v12, v116, 0x3e0293ee, v2
	v_fmamk_f32 v13, v117, 0x3e0293ee, v2
	v_fmamk_f32 v14, v118, 0x3e0293ee, v2
	v_fmamk_f32 v15, v119, 0x3e0293ee, v2
	v_fmamk_f32 v18, v120, 0x3e0293ee, v2
	v_fmamk_f32 v19, v121, 0x3e0293ee, v2
	v_fmamk_f32 v20, v122, 0x3e0293ee, v2
	v_fmamk_f32 v21, v123, 0x3e0293ee, v2
	v_fmamk_f32 v22, v124, 0x3e0293ee, v2
	v_fmamk_f32 v23, v125, 0x3e0293ee, v2
	v_fmamk_f32 v24, v126, 0x3e0293ee, v2
	v_fmamk_f32 v25, v127, 0x3e0293ee, v2
	s_add_u32 s56, s56, 0x8000
	v_exp_f32_e32 v230, v8
	v_exp_f32_e32 v232, v9
	v_exp_f32_e32 v228, v10
	v_exp_f32_e32 v231, v11
	v_exp_f32_e32 v226, v12
	v_exp_f32_e32 v229, v13
	v_exp_f32_e32 v225, v14
	v_exp_f32_e32 v227, v15
	v_exp_f32_e32 v222, v18
	v_exp_f32_e32 v224, v19
	v_exp_f32_e32 v220, v20
	v_exp_f32_e32 v223, v21
	v_exp_f32_e32 v218, v22
	v_exp_f32_e32 v221, v23
	v_exp_f32_e32 v217, v24
	v_exp_f32_e32 v219, v25
	s_addc_u32 s57, s57, 0
	s_add_i32 s4, s45, 2
	v_add_f32_e32 v1, v1, v3
	s_add_u32 s70, s70, 0x8000
	s_waitcnt vmcnt(4) lgkmcnt(0)
	s_barrier
	v_fmac_f32_e32 v1, v213, v205
	v_add_f32_e32 v205, v5, v6
	s_addc_u32 s71, s71, 0
	v_fmac_f32_e32 v205, v1, v4
	v_pk_fma_f32 v[142:143], v[110:111], s[12:13], v[2:3] op_sel_hi:[1,0,0]
	v_pk_fma_f32 v[140:141], v[108:109], s[12:13], v[2:3] op_sel_hi:[1,0,0]
	v_pk_fma_f32 v[138:139], v[106:107], s[12:13], v[2:3] op_sel_hi:[1,0,0]
	v_pk_fma_f32 v[136:137], v[104:105], s[12:13], v[2:3] op_sel_hi:[1,0,0]
	v_pk_fma_f32 v[134:135], v[102:103], s[12:13], v[2:3] op_sel_hi:[1,0,0]
	v_pk_fma_f32 v[132:133], v[100:101], s[12:13], v[2:3] op_sel_hi:[1,0,0]
	v_pk_fma_f32 v[130:131], v[98:99], s[12:13], v[2:3] op_sel_hi:[1,0,0]
	v_pk_fma_f32 v[128:129], v[96:97], s[12:13], v[2:3] op_sel_hi:[1,0,0]
	s_cmp_ge_i32 s4, s21
	s_cbranch_scc1 .LBB0_321
	s_mov_b32 s45, s4
	s_mov_b32 s72, s69
	s_mov_b32 s69, s77
	v_mov_b32_e32 v213, v7
	s_branch .LBB0_309
.Lattn0_slowA:
	v_sub_f32_e32 v4, v214, v2
	v_mul_f32_e32 v4, 0x3e0293ee, v4
	v_exp_f32_e32 v4, v4
	s_nop 0
	v_cmp_gt_f32_e32 vcc, 1.0, v4
	s_cbranch_vccz .Lattn0_backA
	s_and_saveexec_b64 s[72:73], s[2:3]
	ds_write_b32 v204, v4 offset:128
	s_or_b64 exec, exec, s[72:73]
	s_waitcnt lgkmcnt(0)
	ds_read_b128 v[6:9], v203 offset:224
	ds_read_b128 v[10:13], v203 offset:192
	ds_read_b128 v[18:21], v203 offset:160
	ds_read_b128 v[22:25], v203 offset:128
	s_waitcnt lgkmcnt(3)
	v_pk_mul_f32 v[46:47], v[46:47], v[8:9]
	s_waitcnt lgkmcnt(2)
	v_pk_mul_f32 v[42:43], v[42:43], v[12:13]
	s_waitcnt lgkmcnt(1)
	v_pk_mul_f32 v[38:39], v[38:39], v[20:21]
	s_waitcnt lgkmcnt(0)
	v_pk_mul_f32 v[34:35], v[34:35], v[24:25]
	v_pk_mul_f32 v[44:45], v[44:45], v[6:7]
	v_pk_mul_f32 v[40:41], v[40:41], v[10:11]
	v_pk_mul_f32 v[36:37], v[36:37], v[18:19]
	v_pk_mul_f32 v[32:33], v[32:33], v[22:23]
	v_pk_mul_f32 v[62:63], v[62:63], v[8:9]
	v_pk_mul_f32 v[58:59], v[58:59], v[12:13]
	v_pk_mul_f32 v[54:55], v[54:55], v[20:21]
	v_pk_mul_f32 v[50:51], v[50:51], v[24:25]
	v_pk_mul_f32 v[60:61], v[60:61], v[6:7]
	v_pk_mul_f32 v[56:57], v[56:57], v[10:11]
	v_pk_mul_f32 v[52:53], v[52:53], v[18:19]
	v_pk_mul_f32 v[48:49], v[48:49], v[22:23]
	v_pk_mul_f32 v[78:79], v[78:79], v[8:9]
	v_pk_mul_f32 v[74:75], v[74:75], v[12:13]
	v_pk_mul_f32 v[70:71], v[70:71], v[20:21]
	v_pk_mul_f32 v[66:67], v[66:67], v[24:25]
	v_pk_mul_f32 v[76:77], v[76:77], v[6:7]
	v_pk_mul_f32 v[72:73], v[72:73], v[10:11]
	v_pk_mul_f32 v[68:69], v[68:69], v[18:19]
	v_pk_mul_f32 v[64:65], v[64:65], v[22:23]
	v_pk_mul_f32 v[94:95], v[94:95], v[8:9]
	v_pk_mul_f32 v[90:91], v[90:91], v[12:13]
	v_pk_mul_f32 v[86:87], v[86:87], v[20:21]
	v_pk_mul_f32 v[82:83], v[82:83], v[24:25]
	v_pk_mul_f32 v[92:93], v[92:93], v[6:7]
	v_pk_mul_f32 v[88:89], v[88:89], v[10:11]
	v_pk_mul_f32 v[84:85], v[84:85], v[18:19]
	v_pk_mul_f32 v[80:81], v[80:81], v[22:23]
	s_branch .Lattn0_backA
.Lattn0_slowB:
	v_sub_f32_e32 v7, v2, v8
	v_mul_f32_e32 v7, 0x3e0293ee, v7
	v_exp_f32_e32 v7, v7
	v_mov_b32_e32 v214, v8
	v_cmp_gt_f32_e32 vcc, 1.0, v7
	s_cbranch_vccz .Lattn0_backB
	s_and_saveexec_b64 s[72:73], s[2:3]
	ds_write_b32 v204, v7 offset:128
	s_or_b64 exec, exec, s[72:73]
	s_waitcnt lgkmcnt(0)
	ds_read_b128 v[10:13], v203 offset:224
	ds_read_b128 v[18:21], v203 offset:192
	ds_read_b128 v[22:25], v203 offset:160
	ds_read_b128 v[26:29], v203 offset:128
	s_waitcnt lgkmcnt(3)
	v_pk_mul_f32 v[46:47], v[46:47], v[12:13]
	s_waitcnt lgkmcnt(2)
	v_pk_mul_f32 v[42:43], v[42:43], v[20:21]
	s_waitcnt lgkmcnt(1)
	v_pk_mul_f32 v[38:39], v[38:39], v[24:25]
	s_waitcnt lgkmcnt(0)
	v_pk_mul_f32 v[34:35], v[34:35], v[28:29]
	v_pk_mul_f32 v[44:45], v[44:45], v[10:11]
	v_pk_mul_f32 v[40:41], v[40:41], v[18:19]
	v_pk_mul_f32 v[36:37], v[36:37], v[22:23]
	v_pk_mul_f32 v[32:33], v[32:33], v[26:27]
	v_pk_mul_f32 v[62:63], v[62:63], v[12:13]
	v_pk_mul_f32 v[58:59], v[58:59], v[20:21]
	v_pk_mul_f32 v[54:55], v[54:55], v[24:25]
	v_pk_mul_f32 v[50:51], v[50:51], v[28:29]
	v_pk_mul_f32 v[60:61], v[60:61], v[10:11]
	v_pk_mul_f32 v[56:57], v[56:57], v[18:19]
	v_pk_mul_f32 v[52:53], v[52:53], v[22:23]
	v_pk_mul_f32 v[48:49], v[48:49], v[26:27]
	v_pk_mul_f32 v[78:79], v[78:79], v[12:13]
	v_pk_mul_f32 v[74:75], v[74:75], v[20:21]
	v_pk_mul_f32 v[70:71], v[70:71], v[24:25]
	v_pk_mul_f32 v[66:67], v[66:67], v[28:29]
	v_pk_mul_f32 v[76:77], v[76:77], v[10:11]
	v_pk_mul_f32 v[72:73], v[72:73], v[18:19]
	v_pk_mul_f32 v[68:69], v[68:69], v[22:23]
	v_pk_mul_f32 v[64:65], v[64:65], v[26:27]
	v_pk_mul_f32 v[94:95], v[94:95], v[12:13]
	v_pk_mul_f32 v[90:91], v[90:91], v[20:21]
	v_pk_mul_f32 v[86:87], v[86:87], v[24:25]
	v_pk_mul_f32 v[82:83], v[82:83], v[28:29]
	v_pk_mul_f32 v[92:93], v[92:93], v[10:11]
	v_pk_mul_f32 v[88:89], v[88:89], v[18:19]
	v_pk_mul_f32 v[84:85], v[84:85], v[22:23]
	v_pk_mul_f32 v[80:81], v[80:81], v[26:27]
	s_branch .Lattn0_backB
